# diff fast block: temp+copy pairs of the ALiBi accumulator init folded into direct writes (42 v_mov removed per 6 steps)
# speedup vs baseline: 1.0037x; 1.0037x over previous
.Ldf_fast:
	s_add_i32 s0, s43, 2
	s_waitcnt vmcnt(4) lgkmcnt(0)
	s_barrier
	s_add_i32 s20, s58, s43
	s_cmp_lt_i32 s20, s89
	v_mfma_f32_32x32x16_bf16 v[2:17], v[158:161], v[182:185], v[2:17]
	v_subrev_u32_e32 v198, 64, v197
	s_cselect_b64 s[26:27], -1, 0
	v_cvt_f32_i32_e32 v98, v198
	v_cndmask_b32_e64 v188, -v193, v193, s[26:27]
	v_add_u32_e32 v199, s15, v240
	ds_read_b64_tr_b16 v[200:201], v199 offset:51200
	ds_read_b64_tr_b16 v[202:203], v199 offset:51712
	v_fma_f32 v186, v188, v98, -v233
	v_exp_f32_e32 v66, v66
	v_exp_f32_e32 v67, v67
	v_fma_f32 v114, 0, v188, v186
	v_fmamk_f32 v98, v188, 0x42000000, v186
	v_add_f32_e32 v115, v188, v186
	v_mfma_f32_32x32x16_bf16 v[2:17], v[154:157], v[178:181], v[2:17]
	ds_read_b64_tr_b16 v[182:183], v199 offset:52224
	ds_read_b64_tr_b16 v[184:185], v199 offset:52736
	v_fmamk_f32 v99, v188, 0x42040000, v186
	v_fma_f32 v116, 2.0, v188, v186
	v_exp_f32_e32 v68, v68
	v_exp_f32_e32 v69, v69
	s_waitcnt lgkmcnt(2)
	v_mfma_f32_32x32x16_bf16 v[2:17], v[150:153], v[200:203], v[2:17]
	ds_read_b64_tr_b16 v[178:179], v199 offset:53248
	ds_read_b64_tr_b16 v[180:181], v199 offset:53760
	v_add_f32_e32 v187, v187, v66
	v_fmamk_f32 v100, v188, 0x42080000, v186
	v_fmamk_f32 v117, v188, 0x40400000, v186
	v_cvt_pk_bf16_f32 v174, v66, v67
	v_add_f32_e32 v187, v67, v187
	v_exp_f32_e32 v70, v70
	s_waitcnt lgkmcnt(2)
	v_mfma_f32_32x32x16_bf16 v[2:17], v[146:149], v[182:185], v[2:17]
	ds_read_b64_tr_b16 v[200:201], v199 offset:54272
	ds_read_b64_tr_b16 v[202:203], v199 offset:54784
	v_fma_f32 v101, v188, s16, v186
	v_fma_f32 v102, v188, s17, v186
	v_fmamk_f32 v118, v188, 0x41000000, v186
	v_exp_f32_e32 v71, v71
	v_add_f32_e32 v187, v187, v68
	s_waitcnt lgkmcnt(2)
	v_mfma_f32_32x32x16_bf16 v[18:33], v[158:161], v[178:181], v[18:33]
	ds_read_b64_tr_b16 v[182:183], v199 offset:55296
	ds_read_b64_tr_b16 v[184:185], v199 offset:55808
	v_fmamk_f32 v119, v188, 0x41100000, v186
	v_fmamk_f32 v103, v188, 0x42240000, v186
	v_cvt_pk_bf16_f32 v175, v68, v69
	v_add_f32_e32 v187, v187, v69
	v_exp_f32_e32 v72, v72
	s_waitcnt lgkmcnt(2)
	v_mfma_f32_32x32x16_bf16 v[18:33], v[154:157], v[200:203], v[18:33]
	ds_read_b64_tr_b16 v[178:179], v199 offset:56320
	ds_read_b64_tr_b16 v[180:181], v199 offset:56832
	v_fmamk_f32 v120, v188, 0x41200000, v186
	v_fmamk_f32 v104, v188, 0x42280000, v186
	v_exp_f32_e32 v73, v73
	v_add_f32_e32 v187, v187, v70
	v_cvt_pk_bf16_f32 v176, v70, v71
	s_waitcnt lgkmcnt(2)
	v_mfma_f32_32x32x16_bf16 v[18:33], v[150:153], v[182:185], v[18:33]
	ds_read_b64_tr_b16 v[200:201], v199 offset:57344
	ds_read_b64_tr_b16 v[202:203], v199 offset:57856
	v_fmamk_f32 v121, v188, 0x41300000, v186
	v_fmamk_f32 v105, v188, 0x422c0000, v186
	v_add_f32_e32 v182, v187, v71
	v_exp_f32_e32 v74, v74
	v_exp_f32_e32 v75, v75
	s_waitcnt lgkmcnt(2)
	v_mfma_f32_32x32x16_bf16 v[18:33], v[146:149], v[178:181], v[18:33]
	ds_read_b64_tr_b16 v[204:205], v199 offset:58368
	ds_read_b64_tr_b16 v[206:207], v199 offset:58880
	v_add_f32_e32 v178, v182, v72
	v_fmamk_f32 v106, v188, 0x42400000, v186
	v_fma_f32 v122, v188, s48, v186
	v_fma_f32 v123, v188, s49, v186
	v_cvt_pk_bf16_f32 v177, v72, v73
	v_add_f32_e32 v187, v73, v178
	s_waitcnt lgkmcnt(2)
	v_mfma_f32_32x32x16_bf16 v[34:49], v[158:161], v[200:203], v[34:49]
	ds_read_b64_tr_b16 v[182:183], v199 offset:59392
	ds_read_b64_tr_b16 v[184:185], v199 offset:59904
	v_fmamk_f32 v107, v188, 0x42440000, v186
	v_fmamk_f32 v124, v188, 0x41900000, v186
	v_exp_f32_e32 v76, v76
	v_exp_f32_e32 v77, v77
	s_waitcnt lgkmcnt(2)
	v_mfma_f32_32x32x16_bf16 v[34:49], v[154:157], v[204:207], v[34:49]
	ds_read_b64_tr_b16 v[178:179], v199 offset:60416
	ds_read_b64_tr_b16 v[180:181], v199 offset:60928
	v_add_f32_e32 v187, v187, v74
	v_fmamk_f32 v108, v188, 0x42480000, v186
	v_fmamk_f32 v125, v188, 0x41980000, v186
	v_cvt_pk_bf16_f32 v170, v74, v75
	v_add_f32_e32 v200, v75, v187
	v_exp_f32_e32 v78, v78
	s_add_u32 s6, s76, s62
	s_addc_u32 s7, s77, s63
	s_add_u32 s26, s6, 0x30000
	s_addc_u32 s27, s7, 0
	s_add_u32 s6, s78, s62
	s_addc_u32 s7, s79, s63
	s_add_u32 s70, s6, 0x30000
	s_addc_u32 s71, s7, 0
	s_add_i32 s6, 0, s59
	s_add_i32 s7, s81, s90
	s_add_u32 s84, s26, 0x8000
	s_addc_u32 s85, s27, 0
	s_add_i32 s15, s6, 0x2000
	s_mov_b32 m0, s6
	s_nop 0
	global_load_lds_dwordx4 v191, s[26:27]
	s_mov_b32 m0, s15
	s_nop 0
	global_load_lds_dwordx4 v191, s[84:85]
	s_mov_b32 m0, s21
	s_add_u32 s26, s70, 0x80
	s_addc_u32 s27, s71, 0
	s_add_i32 s6, s7, 0x2000
	s_mov_b32 m0, s7
	s_nop 0
	global_load_lds_dwordx4 v192, s[70:71]
	s_mov_b32 m0, s6
	s_nop 0
	global_load_lds_dwordx4 v192, s[26:27]
	s_mov_b32 m0, s15
	s_waitcnt lgkmcnt(2)
	v_mfma_f32_32x32x16_bf16 v[34:49], v[150:153], v[182:185], v[34:49]
	ds_read_b64_tr_b16 v[202:203], v199 offset:61440
	ds_read_b64_tr_b16 v[204:205], v199 offset:61952
	v_fma_f32 v109, v188, s56, v186
	v_fma_f32 v110, v188, s57, v186
	v_fmamk_f32 v126, v188, 0x41c00000, v186
	v_exp_f32_e32 v79, v79
	v_add_f32_e32 v187, v200, v76
	s_waitcnt lgkmcnt(2)
	v_mfma_f32_32x32x16_bf16 v[34:49], v[146:149], v[178:181], v[34:49]
	ds_read_b64_tr_b16 v[182:183], v199 offset:62464
	ds_read_b64_tr_b16 v[184:185], v199 offset:62976
	v_fmamk_f32 v127, v188, 0x41c80000, v186
	v_fmamk_f32 v111, v188, 0x42640000, v186
	v_cvt_pk_bf16_f32 v171, v76, v77
	v_add_f32_e32 v187, v187, v77
	v_exp_f32_e32 v80, v80
	s_waitcnt lgkmcnt(2)
	v_mfma_f32_32x32x16_bf16 v[50:65], v[158:161], v[202:205], v[50:65]
	ds_read_b64_tr_b16 v[178:179], v199 offset:63488
	ds_read_b64_tr_b16 v[180:181], v199 offset:64000
	v_fmamk_f32 v128, v188, 0x41d00000, v186
	v_fmamk_f32 v112, v188, 0x42680000, v186
	v_exp_f32_e32 v81, v81
	v_add_f32_e32 v187, v187, v78
	v_cvt_pk_bf16_f32 v172, v78, v79
	s_waitcnt lgkmcnt(2)
	v_mfma_f32_32x32x16_bf16 v[50:65], v[154:157], v[182:185], v[50:65]
	ds_read_b64_tr_b16 v[200:201], v199 offset:64512
	ds_read_b64_tr_b16 v[202:203], v199 offset:65024
	v_fmamk_f32 v129, v188, 0x41d80000, v186
	v_fmamk_f32 v113, v188, 0x426c0000, v186
	v_exp_f32_e32 v82, v82
	v_exp_f32_e32 v83, v83
	v_add_f32_e32 v186, v187, v79
	s_waitcnt lgkmcnt(2)
	v_mfma_f32_32x32x16_bf16 v[50:65], v[150:153], v[178:181], v[50:65]
	ds_read_b128 v[182:185], v190 offset:16384
	v_add_f32_e32 v178, v186, v80
	v_cvt_pk_bf16_f32 v173, v80, v81
	v_add_f32_e32 v186, v81, v178
	v_exp_f32_e32 v84, v84
	v_exp_f32_e32 v85, v85
	s_waitcnt lgkmcnt(1)
	v_mfma_f32_32x32x16_bf16 v[50:65], v[146:149], v[200:203], v[50:65]
	ds_read_b128 v[178:181], v190 offset:24576
	v_add_f32_e32 v186, v186, v82
	v_cvt_pk_bf16_f32 v166, v82, v83
	v_add_f32_e32 v199, v83, v186
	v_exp_f32_e32 v86, v86
	v_exp_f32_e32 v87, v87
	s_waitcnt lgkmcnt(1)
	v_mfma_f32_32x32x16_bf16 v[114:129], v[182:185], v[130:133], v[114:129]
	ds_read_b128 v[186:189], v194 offset:16384
	v_add_f32_e32 v182, v199, v84
	v_cvt_pk_bf16_f32 v167, v84, v85
	v_add_f32_e32 v199, v85, v182
	v_exp_f32_e32 v88, v88
	v_exp_f32_e32 v89, v89
	s_waitcnt lgkmcnt(1)
	v_mfma_f32_32x32x16_bf16 v[98:113], v[178:181], v[130:133], v[98:113]
	ds_read_b128 v[182:185], v194 offset:24576
	v_add_f32_e32 v178, v199, v86
	v_cvt_pk_bf16_f32 v168, v86, v87
	v_add_f32_e32 v199, v87, v178
	v_exp_f32_e32 v90, v90
	v_exp_f32_e32 v91, v91
	s_waitcnt lgkmcnt(1)
	v_mfma_f32_32x32x16_bf16 v[114:129], v[186:189], v[134:137], v[114:129]
	ds_read_b128 v[178:181], v195 offset:16384
	v_add_f32_e32 v186, v199, v88
	v_cvt_pk_bf16_f32 v169, v88, v89
	v_add_f32_e32 v199, v89, v186
	v_exp_f32_e32 v92, v92
	v_exp_f32_e32 v93, v93
	s_waitcnt lgkmcnt(1)
	v_mfma_f32_32x32x16_bf16 v[98:113], v[182:185], v[134:137], v[98:113]
	ds_read_b128 v[186:189], v195 offset:24576
	v_add_f32_e32 v182, v199, v90
	v_cvt_pk_bf16_f32 v162, v90, v91
	v_add_f32_e32 v182, v91, v182
	v_exp_f32_e32 v94, v94
	v_exp_f32_e32 v95, v95
	s_waitcnt lgkmcnt(1)
	v_mfma_f32_32x32x16_bf16 v[114:129], v[178:181], v[138:141], v[114:129]
	ds_read_b128 v[200:203], v196 offset:16384
	v_add_f32_e32 v178, v182, v92
	v_cvt_pk_bf16_f32 v163, v92, v93
	v_add_f32_e32 v178, v93, v178
	v_exp_f32_e32 v96, v96
	v_exp_f32_e32 v97, v97
	s_waitcnt lgkmcnt(1)
	v_mfma_f32_32x32x16_bf16 v[98:113], v[186:189], v[138:141], v[98:113]
	ds_read_b128 v[204:207], v196 offset:24576
	v_add_f32_e32 v165, v178, v94
	v_add_f32_e32 v165, v95, v165
	v_add_f32_e32 v178, v96, v165
	v_cvt_pk_bf16_f32 v164, v94, v95
	v_cvt_pk_bf16_f32 v165, v96, v97
	v_add_f32_e32 v187, v97, v178
	s_waitcnt lgkmcnt(1)
	v_mfma_f32_32x32x16_bf16 v[114:129], v[200:203], v[142:145], v[114:129]
	v_add_u32_e32 v199, s80, v240
	ds_read_b64_tr_b16 v[182:183], v199 offset:49152
	ds_read_b64_tr_b16 v[184:185], v199 offset:49664
	s_waitcnt lgkmcnt(2)
	v_mfma_f32_32x32x16_bf16 v[98:113], v[204:207], v[142:145], v[98:113]
	ds_read_b64_tr_b16 v[178:179], v199 offset:50176
	ds_read_b64_tr_b16 v[180:181], v199 offset:50688
	s_waitcnt vmcnt(4) lgkmcnt(0)
	s_barrier
	s_add_i32 s6, s81, 0x4000
	s_cmp_lg_u32 s81, 0x10000
	s_cselect_b32 s21, s6, 0
	s_add_i32 s20, s20, 1
	s_cmp_lt_i32 s20, s89
	v_mfma_f32_32x32x16_bf16 v[2:17], v[174:177], v[182:185], v[2:17]
	s_cselect_b64 s[6:7], -1, 0
	v_cvt_f32_i32_e32 v66, v197
	v_cndmask_b32_e64 v188, -v193, v193, s[6:7]
	ds_read_b64_tr_b16 v[200:201], v199 offset:51200
	ds_read_b64_tr_b16 v[202:203], v199 offset:51712
	v_fma_f32 v186, v188, v66, -v233
	v_exp_f32_e32 v114, v114
	v_exp_f32_e32 v115, v115
	v_fma_f32 v66, 0, v188, v186
	v_fmamk_f32 v82, v188, 0x42000000, v186
	v_add_f32_e32 v67, v188, v186
	v_mfma_f32_32x32x16_bf16 v[2:17], v[170:173], v[178:181], v[2:17]
	ds_read_b64_tr_b16 v[182:183], v199 offset:52224
	ds_read_b64_tr_b16 v[184:185], v199 offset:52736
	v_fmamk_f32 v83, v188, 0x42040000, v186
	v_fma_f32 v68, 2.0, v188, v186
	v_exp_f32_e32 v116, v116
	v_exp_f32_e32 v117, v117
	s_waitcnt lgkmcnt(2)
	v_mfma_f32_32x32x16_bf16 v[2:17], v[166:169], v[200:203], v[2:17]
	ds_read_b64_tr_b16 v[178:179], v199 offset:53248
	ds_read_b64_tr_b16 v[180:181], v199 offset:53760
	v_add_f32_e32 v187, v187, v114
	v_fmamk_f32 v84, v188, 0x42080000, v186
	v_fmamk_f32 v69, v188, 0x40400000, v186
	v_cvt_pk_bf16_f32 v158, v114, v115
	v_add_f32_e32 v187, v115, v187
	v_exp_f32_e32 v118, v118
	s_waitcnt lgkmcnt(2)
	v_mfma_f32_32x32x16_bf16 v[2:17], v[162:165], v[182:185], v[2:17]
	ds_read_b64_tr_b16 v[200:201], v199 offset:54272
	ds_read_b64_tr_b16 v[202:203], v199 offset:54784
	v_fma_f32 v85, v188, s16, v186
	v_fma_f32 v86, v188, s17, v186
	v_fmamk_f32 v70, v188, 0x41000000, v186
	v_exp_f32_e32 v119, v119
	v_add_f32_e32 v187, v187, v116
	s_waitcnt lgkmcnt(2)
	v_mfma_f32_32x32x16_bf16 v[18:33], v[174:177], v[178:181], v[18:33]
	ds_read_b64_tr_b16 v[182:183], v199 offset:55296
	ds_read_b64_tr_b16 v[184:185], v199 offset:55808
	v_fmamk_f32 v71, v188, 0x41100000, v186
	v_fmamk_f32 v87, v188, 0x42240000, v186
	v_cvt_pk_bf16_f32 v159, v116, v117
	v_add_f32_e32 v187, v187, v117
	v_exp_f32_e32 v120, v120
	s_waitcnt lgkmcnt(2)
	v_mfma_f32_32x32x16_bf16 v[18:33], v[170:173], v[200:203], v[18:33]
	ds_read_b64_tr_b16 v[178:179], v199 offset:56320
	ds_read_b64_tr_b16 v[180:181], v199 offset:56832
	v_fmamk_f32 v72, v188, 0x41200000, v186
	v_fmamk_f32 v88, v188, 0x42280000, v186
	v_exp_f32_e32 v121, v121
	v_add_f32_e32 v187, v187, v118
	v_cvt_pk_bf16_f32 v160, v118, v119
	s_waitcnt lgkmcnt(2)
	v_mfma_f32_32x32x16_bf16 v[18:33], v[166:169], v[182:185], v[18:33]
	ds_read_b64_tr_b16 v[200:201], v199 offset:57344
	ds_read_b64_tr_b16 v[202:203], v199 offset:57856
	v_fmamk_f32 v73, v188, 0x41300000, v186
	v_fmamk_f32 v89, v188, 0x422c0000, v186
	v_add_f32_e32 v182, v187, v119
	v_exp_f32_e32 v122, v122
	v_exp_f32_e32 v123, v123
	s_waitcnt lgkmcnt(2)
	v_mfma_f32_32x32x16_bf16 v[18:33], v[162:165], v[178:181], v[18:33]
	ds_read_b64_tr_b16 v[204:205], v199 offset:58368
	ds_read_b64_tr_b16 v[206:207], v199 offset:58880
	v_add_f32_e32 v178, v182, v120
	v_fmamk_f32 v90, v188, 0x42400000, v186
	v_fma_f32 v74, v188, s48, v186
	v_fma_f32 v75, v188, s49, v186
	v_cvt_pk_bf16_f32 v161, v120, v121
	v_add_f32_e32 v187, v121, v178
	s_waitcnt lgkmcnt(2)
	v_mfma_f32_32x32x16_bf16 v[34:49], v[174:177], v[200:203], v[34:49]
	ds_read_b64_tr_b16 v[182:183], v199 offset:59392
	ds_read_b64_tr_b16 v[184:185], v199 offset:59904
	v_fmamk_f32 v91, v188, 0x42440000, v186
	v_fmamk_f32 v76, v188, 0x41900000, v186
	v_exp_f32_e32 v124, v124
	v_exp_f32_e32 v125, v125
	s_waitcnt lgkmcnt(2)
	v_mfma_f32_32x32x16_bf16 v[34:49], v[170:173], v[204:207], v[34:49]
	ds_read_b64_tr_b16 v[178:179], v199 offset:60416
	ds_read_b64_tr_b16 v[180:181], v199 offset:60928
	v_add_f32_e32 v187, v187, v122
	v_fmamk_f32 v92, v188, 0x42480000, v186
	v_fmamk_f32 v77, v188, 0x41980000, v186
	v_cvt_pk_bf16_f32 v154, v122, v123
	v_add_f32_e32 v198, v123, v187
	v_exp_f32_e32 v126, v126
	s_add_u32 s6, s76, s62
	s_addc_u32 s7, s77, s63
	s_add_u32 s6, s6, 0x40000
	s_addc_u32 s7, s7, 0
	s_add_u32 s15, s78, s62
	s_addc_u32 s20, s79, s63
	s_add_u32 s24, s15, 0x40000
	s_addc_u32 s25, s20, 0
	s_add_i32 s15, 0x4000, s59
	s_add_i32 s20, s21, s90
	s_add_u32 s26, s6, 0x8000
	s_addc_u32 s27, s7, 0
	s_add_i32 s68, s15, 0x2000
	s_mov_b32 m0, s15
	s_nop 0
	global_load_lds_dwordx4 v191, s[6:7]
	s_mov_b32 m0, s68
	s_nop 0
	global_load_lds_dwordx4 v191, s[26:27]
	s_mov_b32 m0, s69
	s_add_u32 s6, s24, 0x80
	s_addc_u32 s7, s25, 0
	s_add_i32 s15, s20, 0x2000
	s_mov_b32 m0, s20
	s_nop 0
	global_load_lds_dwordx4 v192, s[24:25]
	s_mov_b32 m0, s15
	s_nop 0
	global_load_lds_dwordx4 v192, s[6:7]
	s_mov_b32 m0, s26
	s_waitcnt lgkmcnt(2)
	v_mfma_f32_32x32x16_bf16 v[34:49], v[166:169], v[182:185], v[34:49]
	ds_read_b64_tr_b16 v[200:201], v199 offset:61440
	ds_read_b64_tr_b16 v[202:203], v199 offset:61952
	s_add_i32 s6, s80, 0x4000
	s_cmp_lg_u32 s80, 0x10000
	v_fma_f32 v93, v188, s56, v186
	v_fma_f32 v94, v188, s57, v186
	s_cselect_b32 s15, s6, 0
	v_fmamk_f32 v78, v188, 0x41c00000, v186
	v_exp_f32_e32 v127, v127
	v_add_f32_e32 v187, v198, v124
	s_waitcnt lgkmcnt(2)
	v_mfma_f32_32x32x16_bf16 v[34:49], v[162:165], v[178:181], v[34:49]
	ds_read_b64_tr_b16 v[182:183], v199 offset:62464
	ds_read_b64_tr_b16 v[184:185], v199 offset:62976
	v_fmamk_f32 v79, v188, 0x41c80000, v186
	v_fmamk_f32 v95, v188, 0x42640000, v186
	v_cvt_pk_bf16_f32 v155, v124, v125
	v_add_f32_e32 v187, v187, v125
	v_exp_f32_e32 v128, v128
	s_waitcnt lgkmcnt(2)
	v_mfma_f32_32x32x16_bf16 v[50:65], v[174:177], v[200:203], v[50:65]
	ds_read_b64_tr_b16 v[178:179], v199 offset:63488
	ds_read_b64_tr_b16 v[180:181], v199 offset:64000
	v_fmamk_f32 v80, v188, 0x41d00000, v186
	v_fmamk_f32 v96, v188, 0x42680000, v186
	v_exp_f32_e32 v129, v129
	v_add_f32_e32 v187, v187, v126
	v_cvt_pk_bf16_f32 v156, v126, v127
	s_waitcnt lgkmcnt(2)
	v_mfma_f32_32x32x16_bf16 v[50:65], v[170:173], v[182:185], v[50:65]
	ds_read_b64_tr_b16 v[200:201], v199 offset:64512
	ds_read_b64_tr_b16 v[202:203], v199 offset:65024
	v_fmamk_f32 v81, v188, 0x41d80000, v186
	v_fmamk_f32 v97, v188, 0x426c0000, v186
	v_exp_f32_e32 v98, v98
	v_exp_f32_e32 v99, v99
	v_add_f32_e32 v186, v187, v127
	s_waitcnt lgkmcnt(2)
	v_mfma_f32_32x32x16_bf16 v[50:65], v[166:169], v[178:181], v[50:65]
	ds_read_b128 v[182:185], v190 offset:32768
	v_add_f32_e32 v178, v186, v128
	v_cvt_pk_bf16_f32 v157, v128, v129
	v_add_f32_e32 v186, v129, v178
	v_exp_f32_e32 v100, v100
	v_exp_f32_e32 v101, v101
	s_waitcnt lgkmcnt(1)
	v_mfma_f32_32x32x16_bf16 v[50:65], v[162:165], v[200:203], v[50:65]
	ds_read_b128 v[178:181], v190 offset:40960
	v_add_f32_e32 v186, v186, v98
	v_cvt_pk_bf16_f32 v150, v98, v99
	v_add_f32_e32 v198, v99, v186
	v_exp_f32_e32 v102, v102
	v_exp_f32_e32 v103, v103
	s_waitcnt lgkmcnt(1)
	v_mfma_f32_32x32x16_bf16 v[66:81], v[182:185], v[130:133], v[66:81]
	ds_read_b128 v[186:189], v194 offset:32768
	v_add_f32_e32 v182, v198, v100
	v_cvt_pk_bf16_f32 v151, v100, v101
	v_add_f32_e32 v198, v101, v182
	v_exp_f32_e32 v104, v104
	v_exp_f32_e32 v105, v105
	s_waitcnt lgkmcnt(1)
	v_mfma_f32_32x32x16_bf16 v[82:97], v[178:181], v[130:133], v[82:97]
	ds_read_b128 v[182:185], v194 offset:40960
	v_add_f32_e32 v178, v198, v102
	v_cvt_pk_bf16_f32 v152, v102, v103
	v_add_f32_e32 v198, v103, v178
	v_exp_f32_e32 v106, v106
	v_exp_f32_e32 v107, v107
	s_waitcnt lgkmcnt(1)
	v_mfma_f32_32x32x16_bf16 v[66:81], v[186:189], v[134:137], v[66:81]
	ds_read_b128 v[178:181], v195 offset:32768
	v_add_f32_e32 v186, v198, v104
	v_cvt_pk_bf16_f32 v153, v104, v105
	v_add_f32_e32 v198, v105, v186
	v_exp_f32_e32 v108, v108
	v_exp_f32_e32 v109, v109
	s_waitcnt lgkmcnt(1)
	v_mfma_f32_32x32x16_bf16 v[82:97], v[182:185], v[134:137], v[82:97]
	ds_read_b128 v[186:189], v195 offset:40960
	v_add_f32_e32 v182, v198, v106
	v_cvt_pk_bf16_f32 v146, v106, v107
	v_add_f32_e32 v182, v107, v182
	v_exp_f32_e32 v110, v110
	v_exp_f32_e32 v111, v111
	s_waitcnt lgkmcnt(1)
	v_mfma_f32_32x32x16_bf16 v[66:81], v[178:181], v[138:141], v[66:81]
	ds_read_b128 v[198:201], v196 offset:32768
	v_add_f32_e32 v178, v182, v108
	v_cvt_pk_bf16_f32 v147, v108, v109
	v_add_f32_e32 v178, v109, v178
	v_exp_f32_e32 v112, v112
	v_exp_f32_e32 v113, v113
	s_waitcnt lgkmcnt(1)
	v_mfma_f32_32x32x16_bf16 v[82:97], v[186:189], v[138:141], v[82:97]
	ds_read_b128 v[202:205], v196 offset:40960
	v_add_f32_e32 v149, v178, v110
	v_add_f32_e32 v149, v111, v149
	v_add_f32_e32 v178, v112, v149
	v_cvt_pk_bf16_f32 v148, v110, v111
	v_cvt_pk_bf16_f32 v149, v112, v113
	v_add_f32_e32 v187, v113, v178
	s_waitcnt lgkmcnt(1)
	v_mfma_f32_32x32x16_bf16 v[66:81], v[198:201], v[142:145], v[66:81]
	v_add_u32_e32 v180, s15, v240
	ds_read_b64_tr_b16 v[182:183], v180 offset:49152
	ds_read_b64_tr_b16 v[184:185], v180 offset:49664
	s_waitcnt lgkmcnt(2)
	v_mfma_f32_32x32x16_bf16 v[82:97], v[202:205], v[142:145], v[82:97]
	ds_read_b64_tr_b16 v[178:179], v180 offset:50176
	ds_read_b64_tr_b16 v[180:181], v180 offset:50688
	s_add_i32 s6, s15, 0x4000
	s_cmp_lg_u32 s15, 0x10000
	s_cselect_b32 s80, s6, 0
	s_add_i32 s6, s21, 0x4000
	s_cmp_lg_u32 s21, 0x10000
	s_cselect_b32 s81, s6, 0
	s_add_u32 s78, s78, 0x20000
	s_addc_u32 s79, s79, 0
	s_add_u32 s76, s76, 0x20000
	s_addc_u32 s77, s77, 0
	v_add_u32_e32 v197, 0x80, v197
	s_mov_b32 s43, s0
	s_add_i32 s0, s43, 2
	s_waitcnt vmcnt(4) lgkmcnt(0)
	s_barrier
	s_add_i32 s20, s58, s43
	s_cmp_lt_i32 s20, s89
	v_mfma_f32_32x32x16_bf16 v[2:17], v[158:161], v[182:185], v[2:17]
	v_subrev_u32_e32 v198, 64, v197
	s_cselect_b64 s[26:27], -1, 0
	v_cvt_f32_i32_e32 v98, v198
	v_cndmask_b32_e64 v188, -v193, v193, s[26:27]
	v_add_u32_e32 v199, s15, v240
	ds_read_b64_tr_b16 v[200:201], v199 offset:51200
	ds_read_b64_tr_b16 v[202:203], v199 offset:51712
	v_fma_f32 v186, v188, v98, -v233
	v_exp_f32_e32 v66, v66
	v_exp_f32_e32 v67, v67
	v_fma_f32 v114, 0, v188, v186
	v_fmamk_f32 v98, v188, 0x42000000, v186
	v_add_f32_e32 v115, v188, v186
	v_mfma_f32_32x32x16_bf16 v[2:17], v[154:157], v[178:181], v[2:17]
	ds_read_b64_tr_b16 v[182:183], v199 offset:52224
	ds_read_b64_tr_b16 v[184:185], v199 offset:52736
	v_fmamk_f32 v99, v188, 0x42040000, v186
	v_fma_f32 v116, 2.0, v188, v186
	v_exp_f32_e32 v68, v68
	v_exp_f32_e32 v69, v69
	s_waitcnt lgkmcnt(2)
	v_mfma_f32_32x32x16_bf16 v[2:17], v[150:153], v[200:203], v[2:17]
	ds_read_b64_tr_b16 v[178:179], v199 offset:53248
	ds_read_b64_tr_b16 v[180:181], v199 offset:53760
	v_add_f32_e32 v187, v187, v66
	v_fmamk_f32 v100, v188, 0x42080000, v186
	v_fmamk_f32 v117, v188, 0x40400000, v186
	v_cvt_pk_bf16_f32 v174, v66, v67
	v_add_f32_e32 v187, v67, v187
	v_exp_f32_e32 v70, v70
	s_waitcnt lgkmcnt(2)
	v_mfma_f32_32x32x16_bf16 v[2:17], v[146:149], v[182:185], v[2:17]
	ds_read_b64_tr_b16 v[200:201], v199 offset:54272
	ds_read_b64_tr_b16 v[202:203], v199 offset:54784
	v_fma_f32 v101, v188, s16, v186
	v_fma_f32 v102, v188, s17, v186
	v_fmamk_f32 v118, v188, 0x41000000, v186
	v_exp_f32_e32 v71, v71
	v_add_f32_e32 v187, v187, v68
	s_waitcnt lgkmcnt(2)
	v_mfma_f32_32x32x16_bf16 v[18:33], v[158:161], v[178:181], v[18:33]
	ds_read_b64_tr_b16 v[182:183], v199 offset:55296
	ds_read_b64_tr_b16 v[184:185], v199 offset:55808
	v_fmamk_f32 v119, v188, 0x41100000, v186
	v_fmamk_f32 v103, v188, 0x42240000, v186
	v_cvt_pk_bf16_f32 v175, v68, v69
	v_add_f32_e32 v187, v187, v69
	v_exp_f32_e32 v72, v72
	s_waitcnt lgkmcnt(2)
	v_mfma_f32_32x32x16_bf16 v[18:33], v[154:157], v[200:203], v[18:33]
	ds_read_b64_tr_b16 v[178:179], v199 offset:56320
	ds_read_b64_tr_b16 v[180:181], v199 offset:56832
	v_fmamk_f32 v120, v188, 0x41200000, v186
	v_fmamk_f32 v104, v188, 0x42280000, v186
	v_exp_f32_e32 v73, v73
	v_add_f32_e32 v187, v187, v70
	v_cvt_pk_bf16_f32 v176, v70, v71
	s_waitcnt lgkmcnt(2)
	v_mfma_f32_32x32x16_bf16 v[18:33], v[150:153], v[182:185], v[18:33]
	ds_read_b64_tr_b16 v[200:201], v199 offset:57344
	ds_read_b64_tr_b16 v[202:203], v199 offset:57856
	v_fmamk_f32 v121, v188, 0x41300000, v186
	v_fmamk_f32 v105, v188, 0x422c0000, v186
	v_add_f32_e32 v182, v187, v71
	v_exp_f32_e32 v74, v74
	v_exp_f32_e32 v75, v75
	s_waitcnt lgkmcnt(2)
	v_mfma_f32_32x32x16_bf16 v[18:33], v[146:149], v[178:181], v[18:33]
	ds_read_b64_tr_b16 v[204:205], v199 offset:58368
	ds_read_b64_tr_b16 v[206:207], v199 offset:58880
	v_add_f32_e32 v178, v182, v72
	v_fmamk_f32 v106, v188, 0x42400000, v186
	v_fma_f32 v122, v188, s48, v186
	v_fma_f32 v123, v188, s49, v186
	v_cvt_pk_bf16_f32 v177, v72, v73
	v_add_f32_e32 v187, v73, v178
	s_waitcnt lgkmcnt(2)
	v_mfma_f32_32x32x16_bf16 v[34:49], v[158:161], v[200:203], v[34:49]
	ds_read_b64_tr_b16 v[182:183], v199 offset:59392
	ds_read_b64_tr_b16 v[184:185], v199 offset:59904
	v_fmamk_f32 v107, v188, 0x42440000, v186
	v_fmamk_f32 v124, v188, 0x41900000, v186
	v_exp_f32_e32 v76, v76
	v_exp_f32_e32 v77, v77
	s_waitcnt lgkmcnt(2)
	v_mfma_f32_32x32x16_bf16 v[34:49], v[154:157], v[204:207], v[34:49]
	ds_read_b64_tr_b16 v[178:179], v199 offset:60416
	ds_read_b64_tr_b16 v[180:181], v199 offset:60928
	v_add_f32_e32 v187, v187, v74
	v_fmamk_f32 v108, v188, 0x42480000, v186
	v_fmamk_f32 v125, v188, 0x41980000, v186
	v_cvt_pk_bf16_f32 v170, v74, v75
	v_add_f32_e32 v200, v75, v187
	v_exp_f32_e32 v78, v78
	s_add_u32 s6, s76, s62
	s_addc_u32 s7, s77, s63
	s_add_u32 s26, s6, 0x30000
	s_addc_u32 s27, s7, 0
	s_add_u32 s6, s78, s62
	s_addc_u32 s7, s79, s63
	s_add_u32 s70, s6, 0x30000
	s_addc_u32 s71, s7, 0
	s_add_i32 s6, 0x8000, s59
	s_add_i32 s7, s81, s90
	s_add_u32 s84, s26, 0x8000
	s_addc_u32 s85, s27, 0
	s_add_i32 s15, s6, 0x2000
	s_mov_b32 m0, s6
	s_nop 0
	global_load_lds_dwordx4 v191, s[26:27]
	s_mov_b32 m0, s15
	s_nop 0
	global_load_lds_dwordx4 v191, s[84:85]
	s_mov_b32 m0, s21
	s_add_u32 s26, s70, 0x80
	s_addc_u32 s27, s71, 0
	s_add_i32 s6, s7, 0x2000
	s_mov_b32 m0, s7
	s_nop 0
	global_load_lds_dwordx4 v192, s[70:71]
	s_mov_b32 m0, s6
	s_nop 0
	global_load_lds_dwordx4 v192, s[26:27]
	s_mov_b32 m0, s15
	s_waitcnt lgkmcnt(2)
	v_mfma_f32_32x32x16_bf16 v[34:49], v[150:153], v[182:185], v[34:49]
	ds_read_b64_tr_b16 v[202:203], v199 offset:61440
	ds_read_b64_tr_b16 v[204:205], v199 offset:61952
	v_fma_f32 v109, v188, s56, v186
	v_fma_f32 v110, v188, s57, v186
	v_fmamk_f32 v126, v188, 0x41c00000, v186
	v_exp_f32_e32 v79, v79
	v_add_f32_e32 v187, v200, v76
	s_waitcnt lgkmcnt(2)
	v_mfma_f32_32x32x16_bf16 v[34:49], v[146:149], v[178:181], v[34:49]
	ds_read_b64_tr_b16 v[182:183], v199 offset:62464
	ds_read_b64_tr_b16 v[184:185], v199 offset:62976
	v_fmamk_f32 v127, v188, 0x41c80000, v186
	v_fmamk_f32 v111, v188, 0x42640000, v186
	v_cvt_pk_bf16_f32 v171, v76, v77
	v_add_f32_e32 v187, v187, v77
	v_exp_f32_e32 v80, v80
	s_waitcnt lgkmcnt(2)
	v_mfma_f32_32x32x16_bf16 v[50:65], v[158:161], v[202:205], v[50:65]
	ds_read_b64_tr_b16 v[178:179], v199 offset:63488
	ds_read_b64_tr_b16 v[180:181], v199 offset:64000
	v_fmamk_f32 v128, v188, 0x41d00000, v186
	v_fmamk_f32 v112, v188, 0x42680000, v186
	v_exp_f32_e32 v81, v81
	v_add_f32_e32 v187, v187, v78
	v_cvt_pk_bf16_f32 v172, v78, v79
	s_waitcnt lgkmcnt(2)
	v_mfma_f32_32x32x16_bf16 v[50:65], v[154:157], v[182:185], v[50:65]
	ds_read_b64_tr_b16 v[200:201], v199 offset:64512
	ds_read_b64_tr_b16 v[202:203], v199 offset:65024
	v_fmamk_f32 v129, v188, 0x41d80000, v186
	v_fmamk_f32 v113, v188, 0x426c0000, v186
	v_exp_f32_e32 v82, v82
	v_exp_f32_e32 v83, v83
	v_add_f32_e32 v186, v187, v79
	s_waitcnt lgkmcnt(2)
	v_mfma_f32_32x32x16_bf16 v[50:65], v[150:153], v[178:181], v[50:65]
	ds_read_b128 v[182:185], v190
	v_add_f32_e32 v178, v186, v80
	v_cvt_pk_bf16_f32 v173, v80, v81
	v_add_f32_e32 v186, v81, v178
	v_exp_f32_e32 v84, v84
	v_exp_f32_e32 v85, v85
	s_waitcnt lgkmcnt(1)
	v_mfma_f32_32x32x16_bf16 v[50:65], v[146:149], v[200:203], v[50:65]
	ds_read_b128 v[178:181], v190 offset:8192
	v_add_f32_e32 v186, v186, v82
	v_cvt_pk_bf16_f32 v166, v82, v83
	v_add_f32_e32 v199, v83, v186
	v_exp_f32_e32 v86, v86
	v_exp_f32_e32 v87, v87
	s_waitcnt lgkmcnt(1)
	v_mfma_f32_32x32x16_bf16 v[114:129], v[182:185], v[130:133], v[114:129]
	ds_read_b128 v[186:189], v194
	v_add_f32_e32 v182, v199, v84
	v_cvt_pk_bf16_f32 v167, v84, v85
	v_add_f32_e32 v199, v85, v182
	v_exp_f32_e32 v88, v88
	v_exp_f32_e32 v89, v89
	s_waitcnt lgkmcnt(1)
	v_mfma_f32_32x32x16_bf16 v[98:113], v[178:181], v[130:133], v[98:113]
	ds_read_b128 v[182:185], v194 offset:8192
	v_add_f32_e32 v178, v199, v86
	v_cvt_pk_bf16_f32 v168, v86, v87
	v_add_f32_e32 v199, v87, v178
	v_exp_f32_e32 v90, v90
	v_exp_f32_e32 v91, v91
	s_waitcnt lgkmcnt(1)
	v_mfma_f32_32x32x16_bf16 v[114:129], v[186:189], v[134:137], v[114:129]
	ds_read_b128 v[178:181], v195
	v_add_f32_e32 v186, v199, v88
	v_cvt_pk_bf16_f32 v169, v88, v89
	v_add_f32_e32 v199, v89, v186
	v_exp_f32_e32 v92, v92
	v_exp_f32_e32 v93, v93
	s_waitcnt lgkmcnt(1)
	v_mfma_f32_32x32x16_bf16 v[98:113], v[182:185], v[134:137], v[98:113]
	ds_read_b128 v[186:189], v195 offset:8192
	v_add_f32_e32 v182, v199, v90
	v_cvt_pk_bf16_f32 v162, v90, v91
	v_add_f32_e32 v182, v91, v182
	v_exp_f32_e32 v94, v94
	v_exp_f32_e32 v95, v95
	s_waitcnt lgkmcnt(1)
	v_mfma_f32_32x32x16_bf16 v[114:129], v[178:181], v[138:141], v[114:129]
	ds_read_b128 v[200:203], v196
	v_add_f32_e32 v178, v182, v92
	v_cvt_pk_bf16_f32 v163, v92, v93
	v_add_f32_e32 v178, v93, v178
	v_exp_f32_e32 v96, v96
	v_exp_f32_e32 v97, v97
	s_waitcnt lgkmcnt(1)
	v_mfma_f32_32x32x16_bf16 v[98:113], v[186:189], v[138:141], v[98:113]
	ds_read_b128 v[204:207], v196 offset:8192
	v_add_f32_e32 v165, v178, v94
	v_add_f32_e32 v165, v95, v165
	v_add_f32_e32 v178, v96, v165
	v_cvt_pk_bf16_f32 v164, v94, v95
	v_cvt_pk_bf16_f32 v165, v96, v97
	v_add_f32_e32 v187, v97, v178
	s_waitcnt lgkmcnt(1)
	v_mfma_f32_32x32x16_bf16 v[114:129], v[200:203], v[142:145], v[114:129]
	v_add_u32_e32 v199, s80, v240
	ds_read_b64_tr_b16 v[182:183], v199 offset:49152
	ds_read_b64_tr_b16 v[184:185], v199 offset:49664
	s_waitcnt lgkmcnt(2)
	v_mfma_f32_32x32x16_bf16 v[98:113], v[204:207], v[142:145], v[98:113]
	ds_read_b64_tr_b16 v[178:179], v199 offset:50176
	ds_read_b64_tr_b16 v[180:181], v199 offset:50688
	s_waitcnt vmcnt(4) lgkmcnt(0)
	s_barrier
	s_add_i32 s6, s81, 0x4000
	s_cmp_lg_u32 s81, 0x10000
	s_cselect_b32 s21, s6, 0
	s_add_i32 s20, s20, 1
	s_cmp_lt_i32 s20, s89
	v_mfma_f32_32x32x16_bf16 v[2:17], v[174:177], v[182:185], v[2:17]
	s_cselect_b64 s[6:7], -1, 0
	v_cvt_f32_i32_e32 v66, v197
	v_cndmask_b32_e64 v188, -v193, v193, s[6:7]
	ds_read_b64_tr_b16 v[200:201], v199 offset:51200
	ds_read_b64_tr_b16 v[202:203], v199 offset:51712
	v_fma_f32 v186, v188, v66, -v233
	v_exp_f32_e32 v114, v114
	v_exp_f32_e32 v115, v115
	v_fma_f32 v66, 0, v188, v186
	v_fmamk_f32 v82, v188, 0x42000000, v186
	v_add_f32_e32 v67, v188, v186
	v_mfma_f32_32x32x16_bf16 v[2:17], v[170:173], v[178:181], v[2:17]
	ds_read_b64_tr_b16 v[182:183], v199 offset:52224
	ds_read_b64_tr_b16 v[184:185], v199 offset:52736
	v_fmamk_f32 v83, v188, 0x42040000, v186
	v_fma_f32 v68, 2.0, v188, v186
	v_exp_f32_e32 v116, v116
	v_exp_f32_e32 v117, v117
	s_waitcnt lgkmcnt(2)
	v_mfma_f32_32x32x16_bf16 v[2:17], v[166:169], v[200:203], v[2:17]
	ds_read_b64_tr_b16 v[178:179], v199 offset:53248
	ds_read_b64_tr_b16 v[180:181], v199 offset:53760
	v_add_f32_e32 v187, v187, v114
	v_fmamk_f32 v84, v188, 0x42080000, v186
	v_fmamk_f32 v69, v188, 0x40400000, v186
	v_cvt_pk_bf16_f32 v158, v114, v115
	v_add_f32_e32 v187, v115, v187
	v_exp_f32_e32 v118, v118
	s_waitcnt lgkmcnt(2)
	v_mfma_f32_32x32x16_bf16 v[2:17], v[162:165], v[182:185], v[2:17]
	ds_read_b64_tr_b16 v[200:201], v199 offset:54272
	ds_read_b64_tr_b16 v[202:203], v199 offset:54784
	v_fma_f32 v85, v188, s16, v186
	v_fma_f32 v86, v188, s17, v186
	v_fmamk_f32 v70, v188, 0x41000000, v186
	v_exp_f32_e32 v119, v119
	v_add_f32_e32 v187, v187, v116
	s_waitcnt lgkmcnt(2)
	v_mfma_f32_32x32x16_bf16 v[18:33], v[174:177], v[178:181], v[18:33]
	ds_read_b64_tr_b16 v[182:183], v199 offset:55296
	ds_read_b64_tr_b16 v[184:185], v199 offset:55808
	v_fmamk_f32 v71, v188, 0x41100000, v186
	v_fmamk_f32 v87, v188, 0x42240000, v186
	v_cvt_pk_bf16_f32 v159, v116, v117
	v_add_f32_e32 v187, v187, v117
	v_exp_f32_e32 v120, v120
	s_waitcnt lgkmcnt(2)
	v_mfma_f32_32x32x16_bf16 v[18:33], v[170:173], v[200:203], v[18:33]
	ds_read_b64_tr_b16 v[178:179], v199 offset:56320
	ds_read_b64_tr_b16 v[180:181], v199 offset:56832
	v_fmamk_f32 v72, v188, 0x41200000, v186
	v_fmamk_f32 v88, v188, 0x42280000, v186
	v_exp_f32_e32 v121, v121
	v_add_f32_e32 v187, v187, v118
	v_cvt_pk_bf16_f32 v160, v118, v119
	s_waitcnt lgkmcnt(2)
	v_mfma_f32_32x32x16_bf16 v[18:33], v[166:169], v[182:185], v[18:33]
	ds_read_b64_tr_b16 v[200:201], v199 offset:57344
	ds_read_b64_tr_b16 v[202:203], v199 offset:57856
	v_fmamk_f32 v73, v188, 0x41300000, v186
	v_fmamk_f32 v89, v188, 0x422c0000, v186
	v_add_f32_e32 v182, v187, v119
	v_exp_f32_e32 v122, v122
	v_exp_f32_e32 v123, v123
	s_waitcnt lgkmcnt(2)
	v_mfma_f32_32x32x16_bf16 v[18:33], v[162:165], v[178:181], v[18:33]
	ds_read_b64_tr_b16 v[204:205], v199 offset:58368
	ds_read_b64_tr_b16 v[206:207], v199 offset:58880
	v_add_f32_e32 v178, v182, v120
	v_fmamk_f32 v90, v188, 0x42400000, v186
	v_fma_f32 v74, v188, s48, v186
	v_fma_f32 v75, v188, s49, v186
	v_cvt_pk_bf16_f32 v161, v120, v121
	v_add_f32_e32 v187, v121, v178
	s_waitcnt lgkmcnt(2)
	v_mfma_f32_32x32x16_bf16 v[34:49], v[174:177], v[200:203], v[34:49]
	ds_read_b64_tr_b16 v[182:183], v199 offset:59392
	ds_read_b64_tr_b16 v[184:185], v199 offset:59904
	v_fmamk_f32 v91, v188, 0x42440000, v186
	v_fmamk_f32 v76, v188, 0x41900000, v186
	v_exp_f32_e32 v124, v124
	v_exp_f32_e32 v125, v125
	s_waitcnt lgkmcnt(2)
	v_mfma_f32_32x32x16_bf16 v[34:49], v[170:173], v[204:207], v[34:49]
	ds_read_b64_tr_b16 v[178:179], v199 offset:60416
	ds_read_b64_tr_b16 v[180:181], v199 offset:60928
	v_add_f32_e32 v187, v187, v122
	v_fmamk_f32 v92, v188, 0x42480000, v186
	v_fmamk_f32 v77, v188, 0x41980000, v186
	v_cvt_pk_bf16_f32 v154, v122, v123
	v_add_f32_e32 v198, v123, v187
	v_exp_f32_e32 v126, v126
	s_add_u32 s6, s76, s62
	s_addc_u32 s7, s77, s63
	s_add_u32 s6, s6, 0x40000
	s_addc_u32 s7, s7, 0
	s_add_u32 s15, s78, s62
	s_addc_u32 s20, s79, s63
	s_add_u32 s24, s15, 0x40000
	s_addc_u32 s25, s20, 0
	s_add_i32 s15, 0, s59
	s_add_i32 s20, s21, s90
	s_add_u32 s26, s6, 0x8000
	s_addc_u32 s27, s7, 0
	s_add_i32 s68, s15, 0x2000
	s_mov_b32 m0, s15
	s_nop 0
	global_load_lds_dwordx4 v191, s[6:7]
	s_mov_b32 m0, s68
	s_nop 0
	global_load_lds_dwordx4 v191, s[26:27]
	s_mov_b32 m0, s69
	s_add_u32 s6, s24, 0x80
	s_addc_u32 s7, s25, 0
	s_add_i32 s15, s20, 0x2000
	s_mov_b32 m0, s20
	s_nop 0
	global_load_lds_dwordx4 v192, s[24:25]
	s_mov_b32 m0, s15
	s_nop 0
	global_load_lds_dwordx4 v192, s[6:7]
	s_mov_b32 m0, s26
	s_waitcnt lgkmcnt(2)
	v_mfma_f32_32x32x16_bf16 v[34:49], v[166:169], v[182:185], v[34:49]
	ds_read_b64_tr_b16 v[200:201], v199 offset:61440
	ds_read_b64_tr_b16 v[202:203], v199 offset:61952
	s_add_i32 s6, s80, 0x4000
	s_cmp_lg_u32 s80, 0x10000
	v_fma_f32 v93, v188, s56, v186
	v_fma_f32 v94, v188, s57, v186
	s_cselect_b32 s15, s6, 0
	v_fmamk_f32 v78, v188, 0x41c00000, v186
	v_exp_f32_e32 v127, v127
	v_add_f32_e32 v187, v198, v124
	s_waitcnt lgkmcnt(2)
	v_mfma_f32_32x32x16_bf16 v[34:49], v[162:165], v[178:181], v[34:49]
	ds_read_b64_tr_b16 v[182:183], v199 offset:62464
	ds_read_b64_tr_b16 v[184:185], v199 offset:62976
	v_fmamk_f32 v79, v188, 0x41c80000, v186
	v_fmamk_f32 v95, v188, 0x42640000, v186
	v_cvt_pk_bf16_f32 v155, v124, v125
	v_add_f32_e32 v187, v187, v125
	v_exp_f32_e32 v128, v128
	s_waitcnt lgkmcnt(2)
	v_mfma_f32_32x32x16_bf16 v[50:65], v[174:177], v[200:203], v[50:65]
	ds_read_b64_tr_b16 v[178:179], v199 offset:63488
	ds_read_b64_tr_b16 v[180:181], v199 offset:64000
	v_fmamk_f32 v80, v188, 0x41d00000, v186
	v_fmamk_f32 v96, v188, 0x42680000, v186
	v_exp_f32_e32 v129, v129
	v_add_f32_e32 v187, v187, v126
	v_cvt_pk_bf16_f32 v156, v126, v127
	s_waitcnt lgkmcnt(2)
	v_mfma_f32_32x32x16_bf16 v[50:65], v[170:173], v[182:185], v[50:65]
	ds_read_b64_tr_b16 v[200:201], v199 offset:64512
	ds_read_b64_tr_b16 v[202:203], v199 offset:65024
	v_fmamk_f32 v81, v188, 0x41d80000, v186
	v_fmamk_f32 v97, v188, 0x426c0000, v186
	v_exp_f32_e32 v98, v98
	v_exp_f32_e32 v99, v99
	v_add_f32_e32 v186, v187, v127
	s_waitcnt lgkmcnt(2)
	v_mfma_f32_32x32x16_bf16 v[50:65], v[166:169], v[178:181], v[50:65]
	ds_read_b128 v[182:185], v190 offset:16384
	v_add_f32_e32 v178, v186, v128
	v_cvt_pk_bf16_f32 v157, v128, v129
	v_add_f32_e32 v186, v129, v178
	v_exp_f32_e32 v100, v100
	v_exp_f32_e32 v101, v101
	s_waitcnt lgkmcnt(1)
	v_mfma_f32_32x32x16_bf16 v[50:65], v[162:165], v[200:203], v[50:65]
	ds_read_b128 v[178:181], v190 offset:24576
	v_add_f32_e32 v186, v186, v98
	v_cvt_pk_bf16_f32 v150, v98, v99
	v_add_f32_e32 v198, v99, v186
	v_exp_f32_e32 v102, v102
	v_exp_f32_e32 v103, v103
	s_waitcnt lgkmcnt(1)
	v_mfma_f32_32x32x16_bf16 v[66:81], v[182:185], v[130:133], v[66:81]
	ds_read_b128 v[186:189], v194 offset:16384
	v_add_f32_e32 v182, v198, v100
	v_cvt_pk_bf16_f32 v151, v100, v101
	v_add_f32_e32 v198, v101, v182
	v_exp_f32_e32 v104, v104
	v_exp_f32_e32 v105, v105
	s_waitcnt lgkmcnt(1)
	v_mfma_f32_32x32x16_bf16 v[82:97], v[178:181], v[130:133], v[82:97]
	ds_read_b128 v[182:185], v194 offset:24576
	v_add_f32_e32 v178, v198, v102
	v_cvt_pk_bf16_f32 v152, v102, v103
	v_add_f32_e32 v198, v103, v178
	v_exp_f32_e32 v106, v106
	v_exp_f32_e32 v107, v107
	s_waitcnt lgkmcnt(1)
	v_mfma_f32_32x32x16_bf16 v[66:81], v[186:189], v[134:137], v[66:81]
	ds_read_b128 v[178:181], v195 offset:16384
	v_add_f32_e32 v186, v198, v104
	v_cvt_pk_bf16_f32 v153, v104, v105
	v_add_f32_e32 v198, v105, v186
	v_exp_f32_e32 v108, v108
	v_exp_f32_e32 v109, v109
	s_waitcnt lgkmcnt(1)
	v_mfma_f32_32x32x16_bf16 v[82:97], v[182:185], v[134:137], v[82:97]
	ds_read_b128 v[186:189], v195 offset:24576
	v_add_f32_e32 v182, v198, v106
	v_cvt_pk_bf16_f32 v146, v106, v107
	v_add_f32_e32 v182, v107, v182
	v_exp_f32_e32 v110, v110
	v_exp_f32_e32 v111, v111
	s_waitcnt lgkmcnt(1)
	v_mfma_f32_32x32x16_bf16 v[66:81], v[178:181], v[138:141], v[66:81]
	ds_read_b128 v[198:201], v196 offset:16384
	v_add_f32_e32 v178, v182, v108
	v_cvt_pk_bf16_f32 v147, v108, v109
	v_add_f32_e32 v178, v109, v178
	v_exp_f32_e32 v112, v112
	v_exp_f32_e32 v113, v113
	s_waitcnt lgkmcnt(1)
	v_mfma_f32_32x32x16_bf16 v[82:97], v[186:189], v[138:141], v[82:97]
	ds_read_b128 v[202:205], v196 offset:24576
	v_add_f32_e32 v149, v178, v110
	v_add_f32_e32 v149, v111, v149
	v_add_f32_e32 v178, v112, v149
	v_cvt_pk_bf16_f32 v148, v110, v111
	v_cvt_pk_bf16_f32 v149, v112, v113
	v_add_f32_e32 v187, v113, v178
	s_waitcnt lgkmcnt(1)
	v_mfma_f32_32x32x16_bf16 v[66:81], v[198:201], v[142:145], v[66:81]
	v_add_u32_e32 v180, s15, v240
	ds_read_b64_tr_b16 v[182:183], v180 offset:49152
	ds_read_b64_tr_b16 v[184:185], v180 offset:49664
	s_waitcnt lgkmcnt(2)
	v_mfma_f32_32x32x16_bf16 v[82:97], v[202:205], v[142:145], v[82:97]
	ds_read_b64_tr_b16 v[178:179], v180 offset:50176
	ds_read_b64_tr_b16 v[180:181], v180 offset:50688
	s_add_i32 s6, s15, 0x4000
	s_cmp_lg_u32 s15, 0x10000
	s_cselect_b32 s80, s6, 0
	s_add_i32 s6, s21, 0x4000
	s_cmp_lg_u32 s21, 0x10000
	s_cselect_b32 s81, s6, 0
	s_add_u32 s78, s78, 0x20000
	s_addc_u32 s79, s79, 0
	s_add_u32 s76, s76, 0x20000
	s_addc_u32 s77, s77, 0
	v_add_u32_e32 v197, 0x80, v197
	s_mov_b32 s43, s0
	s_add_i32 s0, s43, 2
	s_waitcnt vmcnt(4) lgkmcnt(0)
	s_barrier
	s_add_i32 s20, s58, s43
	s_cmp_lt_i32 s20, s89
	v_mfma_f32_32x32x16_bf16 v[2:17], v[158:161], v[182:185], v[2:17]
	v_subrev_u32_e32 v198, 64, v197
	s_cselect_b64 s[26:27], -1, 0
	v_cvt_f32_i32_e32 v98, v198
	v_cndmask_b32_e64 v188, -v193, v193, s[26:27]
	v_add_u32_e32 v199, s15, v240
	ds_read_b64_tr_b16 v[200:201], v199 offset:51200
	ds_read_b64_tr_b16 v[202:203], v199 offset:51712
	v_fma_f32 v186, v188, v98, -v233
	v_exp_f32_e32 v66, v66
	v_exp_f32_e32 v67, v67
	v_fma_f32 v114, 0, v188, v186
	v_fmamk_f32 v98, v188, 0x42000000, v186
	v_add_f32_e32 v115, v188, v186
	v_mfma_f32_32x32x16_bf16 v[2:17], v[154:157], v[178:181], v[2:17]
	ds_read_b64_tr_b16 v[182:183], v199 offset:52224
	ds_read_b64_tr_b16 v[184:185], v199 offset:52736
	v_fmamk_f32 v99, v188, 0x42040000, v186
	v_fma_f32 v116, 2.0, v188, v186
	v_exp_f32_e32 v68, v68
	v_exp_f32_e32 v69, v69
	s_waitcnt lgkmcnt(2)
	v_mfma_f32_32x32x16_bf16 v[2:17], v[150:153], v[200:203], v[2:17]
	ds_read_b64_tr_b16 v[178:179], v199 offset:53248
	ds_read_b64_tr_b16 v[180:181], v199 offset:53760
	v_add_f32_e32 v187, v187, v66
	v_fmamk_f32 v100, v188, 0x42080000, v186
	v_fmamk_f32 v117, v188, 0x40400000, v186
	v_cvt_pk_bf16_f32 v174, v66, v67
	v_add_f32_e32 v187, v67, v187
	v_exp_f32_e32 v70, v70
	s_waitcnt lgkmcnt(2)
	v_mfma_f32_32x32x16_bf16 v[2:17], v[146:149], v[182:185], v[2:17]
	ds_read_b64_tr_b16 v[200:201], v199 offset:54272
	ds_read_b64_tr_b16 v[202:203], v199 offset:54784
	v_fma_f32 v101, v188, s16, v186
	v_fma_f32 v102, v188, s17, v186
	v_fmamk_f32 v118, v188, 0x41000000, v186
	v_exp_f32_e32 v71, v71
	v_add_f32_e32 v187, v187, v68
	s_waitcnt lgkmcnt(2)
	v_mfma_f32_32x32x16_bf16 v[18:33], v[158:161], v[178:181], v[18:33]
	ds_read_b64_tr_b16 v[182:183], v199 offset:55296
	ds_read_b64_tr_b16 v[184:185], v199 offset:55808
	v_fmamk_f32 v119, v188, 0x41100000, v186
	v_fmamk_f32 v103, v188, 0x42240000, v186
	v_cvt_pk_bf16_f32 v175, v68, v69
	v_add_f32_e32 v187, v187, v69
	v_exp_f32_e32 v72, v72
	s_waitcnt lgkmcnt(2)
	v_mfma_f32_32x32x16_bf16 v[18:33], v[154:157], v[200:203], v[18:33]
	ds_read_b64_tr_b16 v[178:179], v199 offset:56320
	ds_read_b64_tr_b16 v[180:181], v199 offset:56832
	v_fmamk_f32 v120, v188, 0x41200000, v186
	v_fmamk_f32 v104, v188, 0x42280000, v186
	v_exp_f32_e32 v73, v73
	v_add_f32_e32 v187, v187, v70
	v_cvt_pk_bf16_f32 v176, v70, v71
	s_waitcnt lgkmcnt(2)
	v_mfma_f32_32x32x16_bf16 v[18:33], v[150:153], v[182:185], v[18:33]
	ds_read_b64_tr_b16 v[200:201], v199 offset:57344
	ds_read_b64_tr_b16 v[202:203], v199 offset:57856
	v_fmamk_f32 v121, v188, 0x41300000, v186
	v_fmamk_f32 v105, v188, 0x422c0000, v186
	v_add_f32_e32 v182, v187, v71
	v_exp_f32_e32 v74, v74
	v_exp_f32_e32 v75, v75
	s_waitcnt lgkmcnt(2)
	v_mfma_f32_32x32x16_bf16 v[18:33], v[146:149], v[178:181], v[18:33]
	ds_read_b64_tr_b16 v[204:205], v199 offset:58368
	ds_read_b64_tr_b16 v[206:207], v199 offset:58880
	v_add_f32_e32 v178, v182, v72
	v_fmamk_f32 v106, v188, 0x42400000, v186
	v_fma_f32 v122, v188, s48, v186
	v_fma_f32 v123, v188, s49, v186
	v_cvt_pk_bf16_f32 v177, v72, v73
	v_add_f32_e32 v187, v73, v178
	s_waitcnt lgkmcnt(2)
	v_mfma_f32_32x32x16_bf16 v[34:49], v[158:161], v[200:203], v[34:49]
	ds_read_b64_tr_b16 v[182:183], v199 offset:59392
	ds_read_b64_tr_b16 v[184:185], v199 offset:59904
	v_fmamk_f32 v107, v188, 0x42440000, v186
	v_fmamk_f32 v124, v188, 0x41900000, v186
	v_exp_f32_e32 v76, v76
	v_exp_f32_e32 v77, v77
	s_waitcnt lgkmcnt(2)
	v_mfma_f32_32x32x16_bf16 v[34:49], v[154:157], v[204:207], v[34:49]
	ds_read_b64_tr_b16 v[178:179], v199 offset:60416
	ds_read_b64_tr_b16 v[180:181], v199 offset:60928
	v_add_f32_e32 v187, v187, v74
	v_fmamk_f32 v108, v188, 0x42480000, v186
	v_fmamk_f32 v125, v188, 0x41980000, v186
	v_cvt_pk_bf16_f32 v170, v74, v75
	v_add_f32_e32 v200, v75, v187
	v_exp_f32_e32 v78, v78
	s_add_u32 s6, s76, s62
	s_addc_u32 s7, s77, s63
	s_add_u32 s26, s6, 0x30000
	s_addc_u32 s27, s7, 0
	s_add_u32 s6, s78, s62
	s_addc_u32 s7, s79, s63
	s_add_u32 s70, s6, 0x30000
	s_addc_u32 s71, s7, 0
	s_add_i32 s6, 0x4000, s59
	s_add_i32 s7, s81, s90
	s_add_u32 s84, s26, 0x8000
	s_addc_u32 s85, s27, 0
	s_add_i32 s15, s6, 0x2000
	s_mov_b32 m0, s6
	s_nop 0
	global_load_lds_dwordx4 v191, s[26:27]
	s_mov_b32 m0, s15
	s_nop 0
	global_load_lds_dwordx4 v191, s[84:85]
	s_mov_b32 m0, s21
	s_add_u32 s26, s70, 0x80
	s_addc_u32 s27, s71, 0
	s_add_i32 s6, s7, 0x2000
	s_mov_b32 m0, s7
	s_nop 0
	global_load_lds_dwordx4 v192, s[70:71]
	s_mov_b32 m0, s6
	s_nop 0
	global_load_lds_dwordx4 v192, s[26:27]
	s_mov_b32 m0, s15
	s_waitcnt lgkmcnt(2)
	v_mfma_f32_32x32x16_bf16 v[34:49], v[150:153], v[182:185], v[34:49]
	ds_read_b64_tr_b16 v[202:203], v199 offset:61440
	ds_read_b64_tr_b16 v[204:205], v199 offset:61952
	v_fma_f32 v109, v188, s56, v186
	v_fma_f32 v110, v188, s57, v186
	v_fmamk_f32 v126, v188, 0x41c00000, v186
	v_exp_f32_e32 v79, v79
	v_add_f32_e32 v187, v200, v76
	s_waitcnt lgkmcnt(2)
	v_mfma_f32_32x32x16_bf16 v[34:49], v[146:149], v[178:181], v[34:49]
	ds_read_b64_tr_b16 v[182:183], v199 offset:62464
	ds_read_b64_tr_b16 v[184:185], v199 offset:62976
	v_fmamk_f32 v127, v188, 0x41c80000, v186
	v_fmamk_f32 v111, v188, 0x42640000, v186
	v_cvt_pk_bf16_f32 v171, v76, v77
	v_add_f32_e32 v187, v187, v77
	v_exp_f32_e32 v80, v80
	s_waitcnt lgkmcnt(2)
	v_mfma_f32_32x32x16_bf16 v[50:65], v[158:161], v[202:205], v[50:65]
	ds_read_b64_tr_b16 v[178:179], v199 offset:63488
	ds_read_b64_tr_b16 v[180:181], v199 offset:64000
	v_fmamk_f32 v128, v188, 0x41d00000, v186
	v_fmamk_f32 v112, v188, 0x42680000, v186
	v_exp_f32_e32 v81, v81
	v_add_f32_e32 v187, v187, v78
	v_cvt_pk_bf16_f32 v172, v78, v79
	s_waitcnt lgkmcnt(2)
	v_mfma_f32_32x32x16_bf16 v[50:65], v[154:157], v[182:185], v[50:65]
	ds_read_b64_tr_b16 v[200:201], v199 offset:64512
	ds_read_b64_tr_b16 v[202:203], v199 offset:65024
	v_fmamk_f32 v129, v188, 0x41d80000, v186
	v_fmamk_f32 v113, v188, 0x426c0000, v186
	v_exp_f32_e32 v82, v82
	v_exp_f32_e32 v83, v83
	v_add_f32_e32 v186, v187, v79
	s_waitcnt lgkmcnt(2)
	v_mfma_f32_32x32x16_bf16 v[50:65], v[150:153], v[178:181], v[50:65]
	ds_read_b128 v[182:185], v190 offset:32768
	v_add_f32_e32 v178, v186, v80
	v_cvt_pk_bf16_f32 v173, v80, v81
	v_add_f32_e32 v186, v81, v178
	v_exp_f32_e32 v84, v84
	v_exp_f32_e32 v85, v85
	s_waitcnt lgkmcnt(1)
	v_mfma_f32_32x32x16_bf16 v[50:65], v[146:149], v[200:203], v[50:65]
	ds_read_b128 v[178:181], v190 offset:40960
	v_add_f32_e32 v186, v186, v82
	v_cvt_pk_bf16_f32 v166, v82, v83
	v_add_f32_e32 v199, v83, v186
	v_exp_f32_e32 v86, v86
	v_exp_f32_e32 v87, v87
	s_waitcnt lgkmcnt(1)
	v_mfma_f32_32x32x16_bf16 v[114:129], v[182:185], v[130:133], v[114:129]
	ds_read_b128 v[186:189], v194 offset:32768
	v_add_f32_e32 v182, v199, v84
	v_cvt_pk_bf16_f32 v167, v84, v85
	v_add_f32_e32 v199, v85, v182
	v_exp_f32_e32 v88, v88
	v_exp_f32_e32 v89, v89
	s_waitcnt lgkmcnt(1)
	v_mfma_f32_32x32x16_bf16 v[98:113], v[178:181], v[130:133], v[98:113]
	ds_read_b128 v[182:185], v194 offset:40960
	v_add_f32_e32 v178, v199, v86
	v_cvt_pk_bf16_f32 v168, v86, v87
	v_add_f32_e32 v199, v87, v178
	v_exp_f32_e32 v90, v90
	v_exp_f32_e32 v91, v91
	s_waitcnt lgkmcnt(1)
	v_mfma_f32_32x32x16_bf16 v[114:129], v[186:189], v[134:137], v[114:129]
	ds_read_b128 v[178:181], v195 offset:32768
	v_add_f32_e32 v186, v199, v88
	v_cvt_pk_bf16_f32 v169, v88, v89
	v_add_f32_e32 v199, v89, v186
	v_exp_f32_e32 v92, v92
	v_exp_f32_e32 v93, v93
	s_waitcnt lgkmcnt(1)
	v_mfma_f32_32x32x16_bf16 v[98:113], v[182:185], v[134:137], v[98:113]
	ds_read_b128 v[186:189], v195 offset:40960
	v_add_f32_e32 v182, v199, v90
	v_cvt_pk_bf16_f32 v162, v90, v91
	v_add_f32_e32 v182, v91, v182
	v_exp_f32_e32 v94, v94
	v_exp_f32_e32 v95, v95
	s_waitcnt lgkmcnt(1)
	v_mfma_f32_32x32x16_bf16 v[114:129], v[178:181], v[138:141], v[114:129]
	ds_read_b128 v[200:203], v196 offset:32768
	v_add_f32_e32 v178, v182, v92
	v_cvt_pk_bf16_f32 v163, v92, v93
	v_add_f32_e32 v178, v93, v178
	v_exp_f32_e32 v96, v96
	v_exp_f32_e32 v97, v97
	s_waitcnt lgkmcnt(1)
	v_mfma_f32_32x32x16_bf16 v[98:113], v[186:189], v[138:141], v[98:113]
	ds_read_b128 v[204:207], v196 offset:40960
	v_add_f32_e32 v165, v178, v94
	v_add_f32_e32 v165, v95, v165
	v_add_f32_e32 v178, v96, v165
	v_cvt_pk_bf16_f32 v164, v94, v95
	v_cvt_pk_bf16_f32 v165, v96, v97
	v_add_f32_e32 v187, v97, v178
	s_waitcnt lgkmcnt(1)
	v_mfma_f32_32x32x16_bf16 v[114:129], v[200:203], v[142:145], v[114:129]
	v_add_u32_e32 v199, s80, v240
	ds_read_b64_tr_b16 v[182:183], v199 offset:49152
	ds_read_b64_tr_b16 v[184:185], v199 offset:49664
	s_waitcnt lgkmcnt(2)
	v_mfma_f32_32x32x16_bf16 v[98:113], v[204:207], v[142:145], v[98:113]
	ds_read_b64_tr_b16 v[178:179], v199 offset:50176
	ds_read_b64_tr_b16 v[180:181], v199 offset:50688
	s_waitcnt vmcnt(4) lgkmcnt(0)
	s_barrier
	s_add_i32 s6, s81, 0x4000
	s_cmp_lg_u32 s81, 0x10000
	s_cselect_b32 s21, s6, 0
	s_add_i32 s20, s20, 1
	s_cmp_lt_i32 s20, s89
	v_mfma_f32_32x32x16_bf16 v[2:17], v[174:177], v[182:185], v[2:17]
	s_cselect_b64 s[6:7], -1, 0
	v_cvt_f32_i32_e32 v66, v197
	v_cndmask_b32_e64 v188, -v193, v193, s[6:7]
	ds_read_b64_tr_b16 v[200:201], v199 offset:51200
	ds_read_b64_tr_b16 v[202:203], v199 offset:51712
	v_fma_f32 v186, v188, v66, -v233
	v_exp_f32_e32 v114, v114
	v_exp_f32_e32 v115, v115
	v_fma_f32 v66, 0, v188, v186
	v_fmamk_f32 v82, v188, 0x42000000, v186
	v_add_f32_e32 v67, v188, v186
	v_mfma_f32_32x32x16_bf16 v[2:17], v[170:173], v[178:181], v[2:17]
	ds_read_b64_tr_b16 v[182:183], v199 offset:52224
	ds_read_b64_tr_b16 v[184:185], v199 offset:52736
	v_fmamk_f32 v83, v188, 0x42040000, v186
	v_fma_f32 v68, 2.0, v188, v186
	v_exp_f32_e32 v116, v116
	v_exp_f32_e32 v117, v117
	s_waitcnt lgkmcnt(2)
	v_mfma_f32_32x32x16_bf16 v[2:17], v[166:169], v[200:203], v[2:17]
	ds_read_b64_tr_b16 v[178:179], v199 offset:53248
	ds_read_b64_tr_b16 v[180:181], v199 offset:53760
	v_add_f32_e32 v187, v187, v114
	v_fmamk_f32 v84, v188, 0x42080000, v186
	v_fmamk_f32 v69, v188, 0x40400000, v186
	v_cvt_pk_bf16_f32 v158, v114, v115
	v_add_f32_e32 v187, v115, v187
	v_exp_f32_e32 v118, v118
	s_waitcnt lgkmcnt(2)
	v_mfma_f32_32x32x16_bf16 v[2:17], v[162:165], v[182:185], v[2:17]
	ds_read_b64_tr_b16 v[200:201], v199 offset:54272
	ds_read_b64_tr_b16 v[202:203], v199 offset:54784
	v_fma_f32 v85, v188, s16, v186
	v_fma_f32 v86, v188, s17, v186
	v_fmamk_f32 v70, v188, 0x41000000, v186
	v_exp_f32_e32 v119, v119
	v_add_f32_e32 v187, v187, v116
	s_waitcnt lgkmcnt(2)
	v_mfma_f32_32x32x16_bf16 v[18:33], v[174:177], v[178:181], v[18:33]
	ds_read_b64_tr_b16 v[182:183], v199 offset:55296
	ds_read_b64_tr_b16 v[184:185], v199 offset:55808
	v_fmamk_f32 v71, v188, 0x41100000, v186
	v_fmamk_f32 v87, v188, 0x42240000, v186
	v_cvt_pk_bf16_f32 v159, v116, v117
	v_add_f32_e32 v187, v187, v117
	v_exp_f32_e32 v120, v120
	s_waitcnt lgkmcnt(2)
	v_mfma_f32_32x32x16_bf16 v[18:33], v[170:173], v[200:203], v[18:33]
	ds_read_b64_tr_b16 v[178:179], v199 offset:56320
	ds_read_b64_tr_b16 v[180:181], v199 offset:56832
	v_fmamk_f32 v72, v188, 0x41200000, v186
	v_fmamk_f32 v88, v188, 0x42280000, v186
	v_exp_f32_e32 v121, v121
	v_add_f32_e32 v187, v187, v118
	v_cvt_pk_bf16_f32 v160, v118, v119
	s_waitcnt lgkmcnt(2)
	v_mfma_f32_32x32x16_bf16 v[18:33], v[166:169], v[182:185], v[18:33]
	ds_read_b64_tr_b16 v[200:201], v199 offset:57344
	ds_read_b64_tr_b16 v[202:203], v199 offset:57856
	v_fmamk_f32 v73, v188, 0x41300000, v186
	v_fmamk_f32 v89, v188, 0x422c0000, v186
	v_add_f32_e32 v182, v187, v119
	v_exp_f32_e32 v122, v122
	v_exp_f32_e32 v123, v123
	s_waitcnt lgkmcnt(2)
	v_mfma_f32_32x32x16_bf16 v[18:33], v[162:165], v[178:181], v[18:33]
	ds_read_b64_tr_b16 v[204:205], v199 offset:58368
	ds_read_b64_tr_b16 v[206:207], v199 offset:58880
	v_add_f32_e32 v178, v182, v120
	v_fmamk_f32 v90, v188, 0x42400000, v186
	v_fma_f32 v74, v188, s48, v186
	v_fma_f32 v75, v188, s49, v186
	v_cvt_pk_bf16_f32 v161, v120, v121
	v_add_f32_e32 v187, v121, v178
	s_waitcnt lgkmcnt(2)
	v_mfma_f32_32x32x16_bf16 v[34:49], v[174:177], v[200:203], v[34:49]
	ds_read_b64_tr_b16 v[182:183], v199 offset:59392
	ds_read_b64_tr_b16 v[184:185], v199 offset:59904
	v_fmamk_f32 v91, v188, 0x42440000, v186
	v_fmamk_f32 v76, v188, 0x41900000, v186
	v_exp_f32_e32 v124, v124
	v_exp_f32_e32 v125, v125
	s_waitcnt lgkmcnt(2)
	v_mfma_f32_32x32x16_bf16 v[34:49], v[170:173], v[204:207], v[34:49]
	ds_read_b64_tr_b16 v[178:179], v199 offset:60416
	ds_read_b64_tr_b16 v[180:181], v199 offset:60928
	v_add_f32_e32 v187, v187, v122
	v_fmamk_f32 v92, v188, 0x42480000, v186
	v_fmamk_f32 v77, v188, 0x41980000, v186
	v_cvt_pk_bf16_f32 v154, v122, v123
	v_add_f32_e32 v198, v123, v187
	v_exp_f32_e32 v126, v126
	s_add_u32 s6, s76, s62
	s_addc_u32 s7, s77, s63
	s_add_u32 s6, s6, 0x40000
	s_addc_u32 s7, s7, 0
	s_add_u32 s15, s78, s62
	s_addc_u32 s20, s79, s63
	s_add_u32 s24, s15, 0x40000
	s_addc_u32 s25, s20, 0
	s_add_i32 s15, 0x8000, s59
	s_add_i32 s20, s21, s90
	s_add_u32 s26, s6, 0x8000
	s_addc_u32 s27, s7, 0
	s_add_i32 s68, s15, 0x2000
	s_mov_b32 m0, s15
	s_nop 0
	global_load_lds_dwordx4 v191, s[6:7]
	s_mov_b32 m0, s68
	s_nop 0
	global_load_lds_dwordx4 v191, s[26:27]
	s_mov_b32 m0, s69
	s_add_u32 s6, s24, 0x80
	s_addc_u32 s7, s25, 0
	s_add_i32 s15, s20, 0x2000
	s_mov_b32 m0, s20
	s_nop 0
	global_load_lds_dwordx4 v192, s[24:25]
	s_mov_b32 m0, s15
	s_nop 0
	global_load_lds_dwordx4 v192, s[6:7]
	s_mov_b32 m0, s26
	s_waitcnt lgkmcnt(2)
	v_mfma_f32_32x32x16_bf16 v[34:49], v[166:169], v[182:185], v[34:49]
	ds_read_b64_tr_b16 v[200:201], v199 offset:61440
	ds_read_b64_tr_b16 v[202:203], v199 offset:61952
	s_add_i32 s6, s80, 0x4000
	s_cmp_lg_u32 s80, 0x10000
	v_fma_f32 v93, v188, s56, v186
	v_fma_f32 v94, v188, s57, v186
	s_cselect_b32 s15, s6, 0
	v_fmamk_f32 v78, v188, 0x41c00000, v186
	v_exp_f32_e32 v127, v127
	v_add_f32_e32 v187, v198, v124
	s_waitcnt lgkmcnt(2)
	v_mfma_f32_32x32x16_bf16 v[34:49], v[162:165], v[178:181], v[34:49]
	ds_read_b64_tr_b16 v[182:183], v199 offset:62464
	ds_read_b64_tr_b16 v[184:185], v199 offset:62976
	v_fmamk_f32 v79, v188, 0x41c80000, v186
	v_fmamk_f32 v95, v188, 0x42640000, v186
	v_cvt_pk_bf16_f32 v155, v124, v125
	v_add_f32_e32 v187, v187, v125
	v_exp_f32_e32 v128, v128
	s_waitcnt lgkmcnt(2)
	v_mfma_f32_32x32x16_bf16 v[50:65], v[174:177], v[200:203], v[50:65]
	ds_read_b64_tr_b16 v[178:179], v199 offset:63488
	ds_read_b64_tr_b16 v[180:181], v199 offset:64000
	v_fmamk_f32 v80, v188, 0x41d00000, v186
	v_fmamk_f32 v96, v188, 0x42680000, v186
	v_exp_f32_e32 v129, v129
	v_add_f32_e32 v187, v187, v126
	v_cvt_pk_bf16_f32 v156, v126, v127
	s_waitcnt lgkmcnt(2)
	v_mfma_f32_32x32x16_bf16 v[50:65], v[170:173], v[182:185], v[50:65]
	ds_read_b64_tr_b16 v[200:201], v199 offset:64512
	ds_read_b64_tr_b16 v[202:203], v199 offset:65024
	v_fmamk_f32 v81, v188, 0x41d80000, v186
	v_fmamk_f32 v97, v188, 0x426c0000, v186
	v_exp_f32_e32 v98, v98
	v_exp_f32_e32 v99, v99
	v_add_f32_e32 v186, v187, v127
	s_waitcnt lgkmcnt(2)
	v_mfma_f32_32x32x16_bf16 v[50:65], v[166:169], v[178:181], v[50:65]
	ds_read_b128 v[182:185], v190
	v_add_f32_e32 v178, v186, v128
	v_cvt_pk_bf16_f32 v157, v128, v129
	v_add_f32_e32 v186, v129, v178
	v_exp_f32_e32 v100, v100
	v_exp_f32_e32 v101, v101
	s_waitcnt lgkmcnt(1)
	v_mfma_f32_32x32x16_bf16 v[50:65], v[162:165], v[200:203], v[50:65]
	ds_read_b128 v[178:181], v190 offset:8192
	v_add_f32_e32 v186, v186, v98
	v_cvt_pk_bf16_f32 v150, v98, v99
	v_add_f32_e32 v198, v99, v186
	v_exp_f32_e32 v102, v102
	v_exp_f32_e32 v103, v103
	s_waitcnt lgkmcnt(1)
	v_mfma_f32_32x32x16_bf16 v[66:81], v[182:185], v[130:133], v[66:81]
	ds_read_b128 v[186:189], v194
	v_add_f32_e32 v182, v198, v100
	v_cvt_pk_bf16_f32 v151, v100, v101
	v_add_f32_e32 v198, v101, v182
	v_exp_f32_e32 v104, v104
	v_exp_f32_e32 v105, v105
	s_waitcnt lgkmcnt(1)
	v_mfma_f32_32x32x16_bf16 v[82:97], v[178:181], v[130:133], v[82:97]
	ds_read_b128 v[182:185], v194 offset:8192
	v_add_f32_e32 v178, v198, v102
	v_cvt_pk_bf16_f32 v152, v102, v103
	v_add_f32_e32 v198, v103, v178
	v_exp_f32_e32 v106, v106
	v_exp_f32_e32 v107, v107
	s_waitcnt lgkmcnt(1)
	v_mfma_f32_32x32x16_bf16 v[66:81], v[186:189], v[134:137], v[66:81]
	ds_read_b128 v[178:181], v195
	v_add_f32_e32 v186, v198, v104
	v_cvt_pk_bf16_f32 v153, v104, v105
	v_add_f32_e32 v198, v105, v186
	v_exp_f32_e32 v108, v108
	v_exp_f32_e32 v109, v109
	s_waitcnt lgkmcnt(1)
	v_mfma_f32_32x32x16_bf16 v[82:97], v[182:185], v[134:137], v[82:97]
	ds_read_b128 v[186:189], v195 offset:8192
	v_add_f32_e32 v182, v198, v106
	v_cvt_pk_bf16_f32 v146, v106, v107
	v_add_f32_e32 v182, v107, v182
	v_exp_f32_e32 v110, v110
	v_exp_f32_e32 v111, v111
	s_waitcnt lgkmcnt(1)
	v_mfma_f32_32x32x16_bf16 v[66:81], v[178:181], v[138:141], v[66:81]
	ds_read_b128 v[198:201], v196
	v_add_f32_e32 v178, v182, v108
	v_cvt_pk_bf16_f32 v147, v108, v109
	v_add_f32_e32 v178, v109, v178
	v_exp_f32_e32 v112, v112
	v_exp_f32_e32 v113, v113
	s_waitcnt lgkmcnt(1)
	v_mfma_f32_32x32x16_bf16 v[82:97], v[186:189], v[138:141], v[82:97]
	ds_read_b128 v[202:205], v196 offset:8192
	v_add_f32_e32 v149, v178, v110
	v_add_f32_e32 v149, v111, v149
	v_add_f32_e32 v178, v112, v149
	v_cvt_pk_bf16_f32 v148, v110, v111
	v_cvt_pk_bf16_f32 v149, v112, v113
	v_add_f32_e32 v187, v113, v178
	s_waitcnt lgkmcnt(1)
	v_mfma_f32_32x32x16_bf16 v[66:81], v[198:201], v[142:145], v[66:81]
	v_add_u32_e32 v180, s15, v240
	ds_read_b64_tr_b16 v[182:183], v180 offset:49152
	ds_read_b64_tr_b16 v[184:185], v180 offset:49664
	s_waitcnt lgkmcnt(2)
	v_mfma_f32_32x32x16_bf16 v[82:97], v[202:205], v[142:145], v[82:97]
	ds_read_b64_tr_b16 v[178:179], v180 offset:50176
	ds_read_b64_tr_b16 v[180:181], v180 offset:50688
	s_add_i32 s6, s15, 0x4000
	s_cmp_lg_u32 s15, 0x10000
	s_cselect_b32 s80, s6, 0
	s_add_i32 s6, s21, 0x4000
	s_cmp_lg_u32 s21, 0x10000
	s_cselect_b32 s81, s6, 0
	s_add_u32 s78, s78, 0x20000
	s_addc_u32 s79, s79, 0
	s_add_u32 s76, s76, 0x20000
	s_addc_u32 s77, s77, 0
	v_add_u32_e32 v197, 0x80, v197
	s_mov_b32 s43, s0
	s_branch .LBB0_1377
